# SSD item: second head's wave roles swapped (one heavy + one light wave per SIMD) and a static priority raise for the heavy (lt=1) wave; priority reset at the item-advance point
# speedup vs baseline: 1.0057x; 1.0057x over previous
; DI void phase_mix(const Params& P, unsigned char* smem) {
;     ...
;     for (int it = blockIdx.x; it < NIT; it += gridDim.x) {
;         int r = it;
;         if (r < I_SSD) { ssd_pair_item(P, smem, r >> 4, r & 15); __syncthreads(); continue; } r -= I_SSD;
;         if (r < I_KV) { kvprep_item(P, smem, r); continue; } r -= I_KV;
;         if (r < I_CMP) { compress_item(P, smem, r); continue; } r -= I_CMP;
.LBB0_236:
	s_setprio 0
	s_add_i32 s96, s96, s10
	s_add_i32 s76, s76, s10
	s_add_i32 s77, s77, s78
	s_add_i32 s95, s95, s10
	s_cmpk_lt_i32 s96, 0x1200
	s_cbranch_scc0 .LBB0_320

; DI int opaque_tid() { int t = threadIdx.x; asm volatile("" : "+v"(t)); return t; }
; DI void ssd_pair_item(const Params& P, unsigned char* smem, int b, int hp) {
;     const int tid0 = opaque_tid();
;     const int hd = 2 * hp + (tid0 >> 8), g = hp >> 2;
;     const float Aneg = -__expf(P.a_log[hd]), dtb = P.dt_bias[hd], Dsk = P.d_skip[hd];
;     const bf16_t* pbase = P_proj + (size_t)b * TT * LDP;
;     unsigned char* hb = smem + S2_HALF0 + (tid0 >> 8) * S2_HSTRIDE;
;     float* cum = (float*)(hb + S2_CUM); float* wsc = (float*)(hb + S2_WSC); float* dtv = (float*)(hb + S2_DTV); float* wcv = (float*)(hb + S2_WCV);
; DI void phase_mix(const Params& P, unsigned char* smem) {
;     ...
;         if (r < I_SSD) { ssd_pair_item(P, smem, r >> 4, r & 15); __syncthreads(); continue; } r -= I_SSD;
.LBB0_275:
	s_andn2_b64 vcc, exec, s[2:3]
	s_cbranch_vccnz .LBB0_236
	v_lshrrev_b32_e32 v188, 2, v215
	v_and_b32_e32 v188, 64, v188
	v_xor_b32_e32 v188, v215, v188
	v_readfirstlane_b32 s98, v188
	s_bitcmp1_b32 s98, 6
	s_cbranch_scc0 .Lssd_noprio
	s_setprio 1
